# ret_out_item second staging loop unrolled x2 with both loads in flight
# speedup vs baseline: 1.0029x; 1.0029x over previous
; __device__ __forceinline__ void ret_out_item(const P& p, int layer, int item, char* lds) {
;     ...
;   { const u16* kvs = (const u16*)(p.ws + OFF_KVS) + ((long)((b * 4 + h) * 64 + c) * 2) * 4096;
;     for (int e = tid; e < 2 * 64 * 8; e += NTHR) {
;       const int dir = e >> 9, v = (e >> 3) & 63, c8 = (e & 7) * 8;
;       *(bf16x8*)&((dir ? SB : SF)[v * 72 + c8]) = *(const bf16x8*)(kvs + (long)dir * 4096 + v * 64 + c8);
;     } }
.LBB0_264:
	v_ashrrev_i32_e32 v4, 9, v3
	v_ashrrev_i32_e32 v5, 31, v4
	v_bfe_u32 v8, v3, 3, 6
	v_lshlrev_b64 v[4:5], 13, v[4:5]
	v_lshlrev_b32_e32 v6, 1, v2
	v_lshlrev_b32_e32 v200, 7, v8
	v_lshl_add_u64 v[4:5], s[6:7], 0, v[4:5]
	v_lshl_add_u64 v[4:5], v[4:5], 0, v[200:201]
	v_and_b32_e32 v200, 0x70, v6
	v_lshl_add_u64 v[4:5], v[4:5], 0, v[200:201]
	global_load_dwordx4 v[4:7], v[4:5], off
	s_movk_i32 s40, 0x200
	v_cmp_gt_u32_e64 s[40:41], s40, v3
	v_mov_b32_e32 v9, 0xf800
	v_mov_b32_e32 v10, 0xd400
	v_cndmask_b32_e64 v9, v9, v10, s[40:41]
	v_add_u32_e32 v9, 0, v9
	v_mul_u32_u24_e32 v8, 0x90, v8
	v_add3_u32 v8, v9, v8, v200
	v_add_u32_e32 v3, 0x100, v3
	v_add_u32_e32 v2, 0x800, v2
	v_ashrrev_i32_e32 v18, 9, v3
	v_ashrrev_i32_e32 v19, 31, v18
	v_bfe_u32 v22, v3, 3, 6
	v_lshlrev_b64 v[18:19], 13, v[18:19]
	v_lshlrev_b32_e32 v25, 1, v2
	v_lshlrev_b32_e32 v200, 7, v22
	v_lshl_add_u64 v[18:19], s[6:7], 0, v[18:19]
	v_lshl_add_u64 v[18:19], v[18:19], 0, v[200:201]
	v_and_b32_e32 v200, 0x70, v25
	v_lshl_add_u64 v[18:19], v[18:19], 0, v[200:201]
	global_load_dwordx4 v[18:21], v[18:19], off
	s_movk_i32 s40, 0x200
	v_cmp_gt_u32_e64 s[40:41], s40, v3
	v_mov_b32_e32 v23, 0xf800
	v_mov_b32_e32 v24, 0xd400
	v_cndmask_b32_e64 v23, v23, v24, s[40:41]
	v_add_u32_e32 v23, 0, v23
	v_mul_u32_u24_e32 v22, 0x90, v22
	v_add3_u32 v22, v23, v22, v200
	v_cmp_lt_i32_e64 s[40:41], s16, v3
	v_add_u32_e32 v3, 0x100, v3
	v_add_u32_e32 v2, 0x800, v2
	s_or_b64 s[72:73], s[40:41], s[72:73]
	s_waitcnt vmcnt(1)
	ds_write_b128 v8, v[4:7]
	s_waitcnt vmcnt(0)
	ds_write_b128 v22, v[18:21]
	s_andn2_b64 exec, exec, s[72:73]
	s_cbranch_execnz .LBB0_264
	s_branch .LBB0_259
